# G1t: two independent accumulator chains per row (four per row pair) instead of one, shorter dependent packed-FMA chains
# baseline (speedup 1.0000x reference)
;     DEVI int* eidx() const { return (int*)(ws + WS_EIDX); }
;     ...
;     int e[NTL]; float g[NTL], s_u[NTL], s_v[NTL];
; #pragma unroll
;     for (int t = 0; t < NTL; ++t) { e[t] = eidx[(size_t)r * 128 + (tbase + t) * 16 + n16]; g[t] = gwv[(size_t)r * 128 + (tbase + t) * 16 + n16]; }
; #pragma unroll
;     for (int t = 0; t < NTL; ++t) { s_u[t] = su[e[t]]; s_v[t] = sv[e[t]]; }
;     const unsigned char* up[NTL];
; #pragma unroll
;     for (int t = 0; t < NTL; ++t) up[t] = u8 + (size_t)e[t] * D + kq * 16;
;     const unsigned char* hp = h8 + (n16 < 8 ? (size_t)0 : (size_t)M * D) + (size_t)r * D + kq * 16;
;     f32x4_t acc[NTL];
; #pragma unroll
;     for (int t = 0; t < NTL; ++t) acc[t] = (f32x4_t){0.f, 0.f, 0.f, 0.f};
;     u32x4_t b0[NTL], b1[NTL];
; #pragma unroll
;     for (int t = 0; t < NTL; ++t) { b0[t] = *(const u32x4_t*)(up[t]); b1[t] = *(const u32x4_t*)(up[t] + 64); }
;     ...
;     for (int m = 0; m < 16; m += 2) {
;         const u32x4_t a0 = *(const u32x4_t*)(hp + m * 64), a1 = *(const u32x4_t*)(hp + m * 64 + 64);
; #pragma unroll
;         for (int t = 0; t < NTL; ++t) FP8MM(a0, b0[t], acc[t]);
;         if (m + 2 < 16) {
; #pragma unroll
;             for (int t = 0; t < NTL; ++t) b0[t] = *(const u32x4_t*)(up[t] + (m + 2) * 64);
;         }
; #pragma unroll
;         for (int t = 0; t < NTL; ++t) FP8MM(a1, b1[t], acc[t]);
;         if (m + 3 < 16) {
; #pragma unroll
;             for (int t = 0; t < NTL; ++t) b1[t] = *(const u32x4_t*)(up[t] + (m + 3) * 64);
;         }
;     }
.Lg1_loop:
	s_waitcnt vmcnt(16)
	v_cvt_pk_f32_fp8_e32 v[10:11], v180
	v_cvt_pk_f32_fp8_sdwa v[12:13], v180 src0_sel:WORD_1
	v_cvt_pk_f32_fp8_e32 v[14:15], v181
	v_cvt_pk_f32_fp8_sdwa v[16:17], v181 src0_sel:WORD_1
	v_cvt_pk_f32_fp8_e32 v[18:19], v182
	v_cvt_pk_f32_fp8_sdwa v[20:21], v182 src0_sel:WORD_1
	v_cvt_pk_f32_fp8_e32 v[22:23], v183
	v_cvt_pk_f32_fp8_sdwa v[24:25], v183 src0_sel:WORD_1
	v_cvt_pk_f32_fp8_e32 v[26:27], v184
	v_cvt_pk_f32_fp8_sdwa v[28:29], v184 src0_sel:WORD_1
	v_cvt_pk_f32_fp8_e32 v[30:31], v185
	v_cvt_pk_f32_fp8_sdwa v[32:33], v185 src0_sel:WORD_1
	v_cvt_pk_f32_fp8_e32 v[34:35], v186
	v_cvt_pk_f32_fp8_sdwa v[36:37], v186 src0_sel:WORD_1
	v_cvt_pk_f32_fp8_e32 v[38:39], v187
	v_cvt_pk_f32_fp8_sdwa v[40:41], v187 src0_sel:WORD_1
	v_pk_fma_f32 v[10:11], v[26:27], v[8:9], v[10:11]
	v_pk_fma_f32 v[12:13], v[28:29], v[8:9], v[12:13]
	v_pk_fma_f32 v[14:15], v[30:31], v[8:9], v[14:15]
	v_pk_fma_f32 v[16:17], v[32:33], v[8:9], v[16:17]
	v_pk_fma_f32 v[18:19], v[34:35], v[8:9], v[18:19]
	v_pk_fma_f32 v[20:21], v[36:37], v[8:9], v[20:21]
	v_pk_fma_f32 v[22:23], v[38:39], v[8:9], v[22:23]
	v_pk_fma_f32 v[24:25], v[40:41], v[8:9], v[24:25]
	v_lshl_add_u32 v68, v84, 10, v4
	v_lshl_add_u32 v69, v85, 10, v4
	v_lshl_add_u32 v70, v86, 10, v4
	v_lshl_add_u32 v71, v87, 10, v4
	v_lshl_add_u32 v72, v88, 10, v4
	v_lshl_add_u32 v73, v89, 10, v4
	v_lshl_add_u32 v74, v90, 10, v4
	v_lshl_add_u32 v75, v91, 10, v4
	v_lshl_add_u32 v76, v92, 10, v4
	v_lshl_add_u32 v77, v93, 10, v4
	v_lshl_add_u32 v78, v94, 10, v4
	v_lshl_add_u32 v79, v95, 10, v4
	v_lshl_add_u32 v80, v96, 10, v4
	v_lshl_add_u32 v81, v97, 10, v4
	v_lshl_add_u32 v82, v98, 10, v4
	v_lshl_add_u32 v83, v99, 10, v4
	s_add_u32 s9, s22, 1
	s_and_b32 s10, s9, 7
	s_lshr_b32 s11, s9, 3
	s_mul_i32 s23, s10, s21
	s_lshl_b32 s11, s11, 7
	s_add_u32 s16, s60, s23
	s_addc_u32 s17, s61, 0
	s_add_u32 s16, s16, s11
	s_addc_u32 s17, s17, 0
	s_add_u32 s18, s16, 0x1100000
	s_addc_u32 s19, s17, 0
	s_add_u32 s12, s56, s11
	s_addc_u32 s13, s57, 0
	s_add_u32 s9, s22, 2
	s_and_b32 s9, s9, 7
	s_mul_i32 s9, s9, s20
	s_add_u32 s14, s58, s9
	s_addc_u32 s15, s59, 0
	global_load_dwordx4 v[180:183], v4, s[16:17]
	global_load_dwordx4 v[184:187], v4, s[18:19]
	global_load_dwordx4 v[84:87], v5, s[14:15] offset:0
	global_load_dwordx4 v[88:91], v5, s[14:15] offset:16
	global_load_dwordx4 v[92:95], v5, s[14:15] offset:32
	global_load_dwordx4 v[96:99], v5, s[14:15] offset:48
	s_waitcnt vmcnt(20)
	v_cvt_pk_f32_fp8_e32 v[26:27], v120
	v_cvt_pk_f32_fp8_sdwa v[28:29], v120 src0_sel:WORD_1
	v_cvt_pk_f32_fp8_e32 v[30:31], v121
	v_cvt_pk_f32_fp8_sdwa v[32:33], v121 src0_sel:WORD_1
	v_cvt_pk_f32_fp8_e32 v[34:35], v122
	v_cvt_pk_f32_fp8_sdwa v[36:37], v122 src0_sel:WORD_1
	v_cvt_pk_f32_fp8_e32 v[38:39], v123
	v_cvt_pk_f32_fp8_sdwa v[40:41], v123 src0_sel:WORD_1
	v_cvt_pk_f32_fp8_e32 v[42:43], v124
	v_cvt_pk_f32_fp8_sdwa v[44:45], v124 src0_sel:WORD_1
	v_cvt_pk_f32_fp8_e32 v[46:47], v125
	v_cvt_pk_f32_fp8_sdwa v[48:49], v125 src0_sel:WORD_1
	v_cvt_pk_f32_fp8_e32 v[50:51], v126
	v_cvt_pk_f32_fp8_sdwa v[52:53], v126 src0_sel:WORD_1
	v_cvt_pk_f32_fp8_e32 v[54:55], v127
	v_cvt_pk_f32_fp8_sdwa v[56:57], v127 src0_sel:WORD_1
	global_load_dwordx4 v[120:123], v68, s[12:13]
	global_load_dwordx4 v[124:127], v69, s[12:13]
	v_pk_mul_f32 v[58:59], v[26:27], v[10:11]
	v_pk_mul_f32 v[60:61], v[42:43], v[10:11]
	v_pk_mul_f32 v[196:197], v[28:29], v[12:13]
	v_pk_mul_f32 v[198:199], v[44:45], v[12:13]
	v_pk_fma_f32 v[58:59], v[30:31], v[14:15], v[58:59]
	v_pk_fma_f32 v[60:61], v[46:47], v[14:15], v[60:61]
	v_pk_fma_f32 v[196:197], v[32:33], v[16:17], v[196:197]
	v_pk_fma_f32 v[198:199], v[48:49], v[16:17], v[198:199]
	v_pk_fma_f32 v[58:59], v[34:35], v[18:19], v[58:59]
	v_pk_fma_f32 v[60:61], v[50:51], v[18:19], v[60:61]
	v_pk_fma_f32 v[196:197], v[36:37], v[20:21], v[196:197]
	v_pk_fma_f32 v[198:199], v[52:53], v[20:21], v[198:199]
	v_pk_fma_f32 v[58:59], v[38:39], v[22:23], v[58:59]
	v_pk_fma_f32 v[60:61], v[54:55], v[22:23], v[60:61]
	v_pk_fma_f32 v[196:197], v[40:41], v[24:25], v[196:197]
	v_pk_fma_f32 v[198:199], v[56:57], v[24:25], v[198:199]
	v_pk_add_f32 v[58:59], v[58:59], v[196:197]
	v_pk_add_f32 v[60:61], v[60:61], v[198:199]
	v_add_f32_e32 v104, v58, v59
	v_add_f32_e32 v105, v60, v61
	s_waitcnt vmcnt(20)
	v_cvt_pk_f32_fp8_e32 v[26:27], v128
	v_cvt_pk_f32_fp8_sdwa v[28:29], v128 src0_sel:WORD_1
	v_cvt_pk_f32_fp8_e32 v[30:31], v129
	v_cvt_pk_f32_fp8_sdwa v[32:33], v129 src0_sel:WORD_1
	v_cvt_pk_f32_fp8_e32 v[34:35], v130
	v_cvt_pk_f32_fp8_sdwa v[36:37], v130 src0_sel:WORD_1
	v_cvt_pk_f32_fp8_e32 v[38:39], v131
	v_cvt_pk_f32_fp8_sdwa v[40:41], v131 src0_sel:WORD_1
	v_cvt_pk_f32_fp8_e32 v[42:43], v132
	v_cvt_pk_f32_fp8_sdwa v[44:45], v132 src0_sel:WORD_1
	v_cvt_pk_f32_fp8_e32 v[46:47], v133
	v_cvt_pk_f32_fp8_sdwa v[48:49], v133 src0_sel:WORD_1
	v_cvt_pk_f32_fp8_e32 v[50:51], v134
	v_cvt_pk_f32_fp8_sdwa v[52:53], v134 src0_sel:WORD_1
	v_cvt_pk_f32_fp8_e32 v[54:55], v135
	v_cvt_pk_f32_fp8_sdwa v[56:57], v135 src0_sel:WORD_1
	global_load_dwordx4 v[128:131], v70, s[12:13]
	global_load_dwordx4 v[132:135], v71, s[12:13]
	v_pk_mul_f32 v[58:59], v[26:27], v[10:11]
	v_pk_mul_f32 v[60:61], v[42:43], v[10:11]
	v_pk_mul_f32 v[196:197], v[28:29], v[12:13]
	v_pk_mul_f32 v[198:199], v[44:45], v[12:13]
	v_pk_fma_f32 v[58:59], v[30:31], v[14:15], v[58:59]
	v_pk_fma_f32 v[60:61], v[46:47], v[14:15], v[60:61]
	v_pk_fma_f32 v[196:197], v[32:33], v[16:17], v[196:197]
	v_pk_fma_f32 v[198:199], v[48:49], v[16:17], v[198:199]
	v_pk_fma_f32 v[58:59], v[34:35], v[18:19], v[58:59]
	v_pk_fma_f32 v[60:61], v[50:51], v[18:19], v[60:61]
	v_pk_fma_f32 v[196:197], v[36:37], v[20:21], v[196:197]
	v_pk_fma_f32 v[198:199], v[52:53], v[20:21], v[198:199]
	v_pk_fma_f32 v[58:59], v[38:39], v[22:23], v[58:59]
	v_pk_fma_f32 v[60:61], v[54:55], v[22:23], v[60:61]
	v_pk_fma_f32 v[196:197], v[40:41], v[24:25], v[196:197]
	v_pk_fma_f32 v[198:199], v[56:57], v[24:25], v[198:199]
	v_pk_add_f32 v[58:59], v[58:59], v[196:197]
	v_pk_add_f32 v[60:61], v[60:61], v[198:199]
	v_add_f32_e32 v106, v58, v59
	v_add_f32_e32 v107, v60, v61
	s_waitcnt vmcnt(20)
;     ...
;     for (int m = 0; m < 16; m += 2) {
;         const u32x4_t a0 = *(const u32x4_t*)(hp + m * 64), a1 = *(const u32x4_t*)(hp + m * 64 + 64);
; #pragma unroll
;         for (int t = 0; t < NTL; ++t) FP8MM(a0, b0[t], acc[t]);
;         if (m + 2 < 16) {
; #pragma unroll
;             for (int t = 0; t < NTL; ++t) b0[t] = *(const u32x4_t*)(up[t] + (m + 2) * 64);
;         }
; #pragma unroll
;         for (int t = 0; t < NTL; ++t) FP8MM(a1, b1[t], acc[t]);
;         if (m + 3 < 16) {
; #pragma unroll
;             for (int t = 0; t < NTL; ++t) b1[t] = *(const u32x4_t*)(up[t] + (m + 3) * 64);
;         }
;     }
	v_cvt_pk_f32_fp8_e32 v[26:27], v136
	v_cvt_pk_f32_fp8_sdwa v[28:29], v136 src0_sel:WORD_1
	v_cvt_pk_f32_fp8_e32 v[30:31], v137
	v_cvt_pk_f32_fp8_sdwa v[32:33], v137 src0_sel:WORD_1
	v_cvt_pk_f32_fp8_e32 v[34:35], v138
	v_cvt_pk_f32_fp8_sdwa v[36:37], v138 src0_sel:WORD_1
	v_cvt_pk_f32_fp8_e32 v[38:39], v139
	v_cvt_pk_f32_fp8_sdwa v[40:41], v139 src0_sel:WORD_1
	v_cvt_pk_f32_fp8_e32 v[42:43], v140
	v_cvt_pk_f32_fp8_sdwa v[44:45], v140 src0_sel:WORD_1
	v_cvt_pk_f32_fp8_e32 v[46:47], v141
	v_cvt_pk_f32_fp8_sdwa v[48:49], v141 src0_sel:WORD_1
	v_cvt_pk_f32_fp8_e32 v[50:51], v142
	v_cvt_pk_f32_fp8_sdwa v[52:53], v142 src0_sel:WORD_1
	v_cvt_pk_f32_fp8_e32 v[54:55], v143
	v_cvt_pk_f32_fp8_sdwa v[56:57], v143 src0_sel:WORD_1
	global_load_dwordx4 v[136:139], v72, s[12:13]
	global_load_dwordx4 v[140:143], v73, s[12:13]
	v_pk_mul_f32 v[58:59], v[26:27], v[10:11]
	v_pk_mul_f32 v[60:61], v[42:43], v[10:11]
	v_pk_mul_f32 v[196:197], v[28:29], v[12:13]
	v_pk_mul_f32 v[198:199], v[44:45], v[12:13]
	v_pk_fma_f32 v[58:59], v[30:31], v[14:15], v[58:59]
	v_pk_fma_f32 v[60:61], v[46:47], v[14:15], v[60:61]
	v_pk_fma_f32 v[196:197], v[32:33], v[16:17], v[196:197]
	v_pk_fma_f32 v[198:199], v[48:49], v[16:17], v[198:199]
	v_pk_fma_f32 v[58:59], v[34:35], v[18:19], v[58:59]
	v_pk_fma_f32 v[60:61], v[50:51], v[18:19], v[60:61]
	v_pk_fma_f32 v[196:197], v[36:37], v[20:21], v[196:197]
	v_pk_fma_f32 v[198:199], v[52:53], v[20:21], v[198:199]
	v_pk_fma_f32 v[58:59], v[38:39], v[22:23], v[58:59]
	v_pk_fma_f32 v[60:61], v[54:55], v[22:23], v[60:61]
	v_pk_fma_f32 v[196:197], v[40:41], v[24:25], v[196:197]
	v_pk_fma_f32 v[198:199], v[56:57], v[24:25], v[198:199]
	v_pk_add_f32 v[58:59], v[58:59], v[196:197]
	v_pk_add_f32 v[60:61], v[60:61], v[198:199]
	v_add_f32_e32 v108, v58, v59
	v_add_f32_e32 v109, v60, v61
	s_waitcnt vmcnt(20)
	v_cvt_pk_f32_fp8_e32 v[26:27], v144
	v_cvt_pk_f32_fp8_sdwa v[28:29], v144 src0_sel:WORD_1
	v_cvt_pk_f32_fp8_e32 v[30:31], v145
	v_cvt_pk_f32_fp8_sdwa v[32:33], v145 src0_sel:WORD_1
	v_cvt_pk_f32_fp8_e32 v[34:35], v146
	v_cvt_pk_f32_fp8_sdwa v[36:37], v146 src0_sel:WORD_1
	v_cvt_pk_f32_fp8_e32 v[38:39], v147
	v_cvt_pk_f32_fp8_sdwa v[40:41], v147 src0_sel:WORD_1
	v_cvt_pk_f32_fp8_e32 v[42:43], v148
	v_cvt_pk_f32_fp8_sdwa v[44:45], v148 src0_sel:WORD_1
	v_cvt_pk_f32_fp8_e32 v[46:47], v149
	v_cvt_pk_f32_fp8_sdwa v[48:49], v149 src0_sel:WORD_1
	v_cvt_pk_f32_fp8_e32 v[50:51], v150
	v_cvt_pk_f32_fp8_sdwa v[52:53], v150 src0_sel:WORD_1
	v_cvt_pk_f32_fp8_e32 v[54:55], v151
	v_cvt_pk_f32_fp8_sdwa v[56:57], v151 src0_sel:WORD_1
	global_load_dwordx4 v[144:147], v74, s[12:13]
	global_load_dwordx4 v[148:151], v75, s[12:13]
	v_pk_mul_f32 v[58:59], v[26:27], v[10:11]
	v_pk_mul_f32 v[60:61], v[42:43], v[10:11]
	v_pk_mul_f32 v[196:197], v[28:29], v[12:13]
	v_pk_mul_f32 v[198:199], v[44:45], v[12:13]
	v_pk_fma_f32 v[58:59], v[30:31], v[14:15], v[58:59]
	v_pk_fma_f32 v[60:61], v[46:47], v[14:15], v[60:61]
	v_pk_fma_f32 v[196:197], v[32:33], v[16:17], v[196:197]
	v_pk_fma_f32 v[198:199], v[48:49], v[16:17], v[198:199]
	v_pk_fma_f32 v[58:59], v[34:35], v[18:19], v[58:59]
	v_pk_fma_f32 v[60:61], v[50:51], v[18:19], v[60:61]
	v_pk_fma_f32 v[196:197], v[36:37], v[20:21], v[196:197]
	v_pk_fma_f32 v[198:199], v[52:53], v[20:21], v[198:199]
	v_pk_fma_f32 v[58:59], v[38:39], v[22:23], v[58:59]
	v_pk_fma_f32 v[60:61], v[54:55], v[22:23], v[60:61]
	v_pk_fma_f32 v[196:197], v[40:41], v[24:25], v[196:197]
	v_pk_fma_f32 v[198:199], v[56:57], v[24:25], v[198:199]
	v_pk_add_f32 v[58:59], v[58:59], v[196:197]
	v_pk_add_f32 v[60:61], v[60:61], v[198:199]
	v_add_f32_e32 v110, v58, v59
	v_add_f32_e32 v111, v60, v61
	s_waitcnt vmcnt(20)
	v_cvt_pk_f32_fp8_e32 v[26:27], v152
	v_cvt_pk_f32_fp8_sdwa v[28:29], v152 src0_sel:WORD_1
	v_cvt_pk_f32_fp8_e32 v[30:31], v153
	v_cvt_pk_f32_fp8_sdwa v[32:33], v153 src0_sel:WORD_1
	v_cvt_pk_f32_fp8_e32 v[34:35], v154
	v_cvt_pk_f32_fp8_sdwa v[36:37], v154 src0_sel:WORD_1
	v_cvt_pk_f32_fp8_e32 v[38:39], v155
	v_cvt_pk_f32_fp8_sdwa v[40:41], v155 src0_sel:WORD_1
	v_cvt_pk_f32_fp8_e32 v[42:43], v156
	v_cvt_pk_f32_fp8_sdwa v[44:45], v156 src0_sel:WORD_1
	v_cvt_pk_f32_fp8_e32 v[46:47], v157
	v_cvt_pk_f32_fp8_sdwa v[48:49], v157 src0_sel:WORD_1
	v_cvt_pk_f32_fp8_e32 v[50:51], v158
	v_cvt_pk_f32_fp8_sdwa v[52:53], v158 src0_sel:WORD_1
	v_cvt_pk_f32_fp8_e32 v[54:55], v159
	v_cvt_pk_f32_fp8_sdwa v[56:57], v159 src0_sel:WORD_1
	global_load_dwordx4 v[152:155], v76, s[12:13]
	global_load_dwordx4 v[156:159], v77, s[12:13]
	v_pk_mul_f32 v[58:59], v[26:27], v[10:11]
	v_pk_mul_f32 v[60:61], v[42:43], v[10:11]
	v_pk_mul_f32 v[196:197], v[28:29], v[12:13]
	v_pk_mul_f32 v[198:199], v[44:45], v[12:13]
	v_pk_fma_f32 v[58:59], v[30:31], v[14:15], v[58:59]
	v_pk_fma_f32 v[60:61], v[46:47], v[14:15], v[60:61]
	v_pk_fma_f32 v[196:197], v[32:33], v[16:17], v[196:197]
	v_pk_fma_f32 v[198:199], v[48:49], v[16:17], v[198:199]
	v_pk_fma_f32 v[58:59], v[34:35], v[18:19], v[58:59]
	v_pk_fma_f32 v[60:61], v[50:51], v[18:19], v[60:61]
	v_pk_fma_f32 v[196:197], v[36:37], v[20:21], v[196:197]
	v_pk_fma_f32 v[198:199], v[52:53], v[20:21], v[198:199]
	v_pk_fma_f32 v[58:59], v[38:39], v[22:23], v[58:59]
	v_pk_fma_f32 v[60:61], v[54:55], v[22:23], v[60:61]
	v_pk_fma_f32 v[196:197], v[40:41], v[24:25], v[196:197]
	v_pk_fma_f32 v[198:199], v[56:57], v[24:25], v[198:199]
	v_pk_add_f32 v[58:59], v[58:59], v[196:197]
	v_pk_add_f32 v[60:61], v[60:61], v[198:199]
	v_add_f32_e32 v112, v58, v59
	v_add_f32_e32 v113, v60, v61
	s_waitcnt vmcnt(20)
; DEVI float gelu_f(float x) { const float u = 0.7978845608028654f * (x + 0.044715f * x * x * x); return x * __builtin_amdgcn_rcpf(1.f + __expf(-2.f * u)); }
;     ...
;     for (int m = 0; m < 16; m += 2) {
;         const u32x4_t a0 = *(const u32x4_t*)(hp + m * 64), a1 = *(const u32x4_t*)(hp + m * 64 + 64);
; #pragma unroll
;         for (int t = 0; t < NTL; ++t) FP8MM(a0, b0[t], acc[t]);
;         if (m + 2 < 16) {
; #pragma unroll
;             for (int t = 0; t < NTL; ++t) b0[t] = *(const u32x4_t*)(up[t] + (m + 2) * 64);
;         }
; #pragma unroll
;         for (int t = 0; t < NTL; ++t) FP8MM(a1, b1[t], acc[t]);
;         if (m + 3 < 16) {
; #pragma unroll
;             for (int t = 0; t < NTL; ++t) b1[t] = *(const u32x4_t*)(up[t] + (m + 3) * 64);
;         }
;     }
;     ...
; #pragma unroll
;     for (int t = 0; t < NTL; ++t) { const float lo = __shfl_xor(acc[t][0], 32); const float dot = (acc[t][0] + lo * (1.f / 32.f)) * s_u[t];
;         if (kq == 0) pl[t * 16 + n16] = (u32x2_t){(unsigned)e[t], __float_as_uint(g[t] * gelu_f(dot) * s_v[t])}; }
	v_cvt_pk_f32_fp8_e32 v[26:27], v160
	v_cvt_pk_f32_fp8_sdwa v[28:29], v160 src0_sel:WORD_1
	v_cvt_pk_f32_fp8_e32 v[30:31], v161
	v_cvt_pk_f32_fp8_sdwa v[32:33], v161 src0_sel:WORD_1
	v_cvt_pk_f32_fp8_e32 v[34:35], v162
	v_cvt_pk_f32_fp8_sdwa v[36:37], v162 src0_sel:WORD_1
	v_cvt_pk_f32_fp8_e32 v[38:39], v163
	v_cvt_pk_f32_fp8_sdwa v[40:41], v163 src0_sel:WORD_1
	v_cvt_pk_f32_fp8_e32 v[42:43], v164
	v_cvt_pk_f32_fp8_sdwa v[44:45], v164 src0_sel:WORD_1
	v_cvt_pk_f32_fp8_e32 v[46:47], v165
	v_cvt_pk_f32_fp8_sdwa v[48:49], v165 src0_sel:WORD_1
	v_cvt_pk_f32_fp8_e32 v[50:51], v166
	v_cvt_pk_f32_fp8_sdwa v[52:53], v166 src0_sel:WORD_1
	v_cvt_pk_f32_fp8_e32 v[54:55], v167
	v_cvt_pk_f32_fp8_sdwa v[56:57], v167 src0_sel:WORD_1
	global_load_dwordx4 v[160:163], v78, s[12:13]
	global_load_dwordx4 v[164:167], v79, s[12:13]
	v_pk_mul_f32 v[58:59], v[26:27], v[10:11]
	v_pk_mul_f32 v[60:61], v[42:43], v[10:11]
	v_pk_mul_f32 v[196:197], v[28:29], v[12:13]
	v_pk_mul_f32 v[198:199], v[44:45], v[12:13]
	v_pk_fma_f32 v[58:59], v[30:31], v[14:15], v[58:59]
	v_pk_fma_f32 v[60:61], v[46:47], v[14:15], v[60:61]
	v_pk_fma_f32 v[196:197], v[32:33], v[16:17], v[196:197]
	v_pk_fma_f32 v[198:199], v[48:49], v[16:17], v[198:199]
	v_pk_fma_f32 v[58:59], v[34:35], v[18:19], v[58:59]
	v_pk_fma_f32 v[60:61], v[50:51], v[18:19], v[60:61]
	v_pk_fma_f32 v[196:197], v[36:37], v[20:21], v[196:197]
	v_pk_fma_f32 v[198:199], v[52:53], v[20:21], v[198:199]
	v_pk_fma_f32 v[58:59], v[38:39], v[22:23], v[58:59]
	v_pk_fma_f32 v[60:61], v[54:55], v[22:23], v[60:61]
	v_pk_fma_f32 v[196:197], v[40:41], v[24:25], v[196:197]
	v_pk_fma_f32 v[198:199], v[56:57], v[24:25], v[198:199]
	v_pk_add_f32 v[58:59], v[58:59], v[196:197]
	v_pk_add_f32 v[60:61], v[60:61], v[198:199]
	v_add_f32_e32 v114, v58, v59
	v_add_f32_e32 v115, v60, v61
	s_waitcnt vmcnt(20)
	v_cvt_pk_f32_fp8_e32 v[26:27], v168
	v_cvt_pk_f32_fp8_sdwa v[28:29], v168 src0_sel:WORD_1
	v_cvt_pk_f32_fp8_e32 v[30:31], v169
	v_cvt_pk_f32_fp8_sdwa v[32:33], v169 src0_sel:WORD_1
	v_cvt_pk_f32_fp8_e32 v[34:35], v170
	v_cvt_pk_f32_fp8_sdwa v[36:37], v170 src0_sel:WORD_1
	v_cvt_pk_f32_fp8_e32 v[38:39], v171
	v_cvt_pk_f32_fp8_sdwa v[40:41], v171 src0_sel:WORD_1
	v_cvt_pk_f32_fp8_e32 v[42:43], v172
	v_cvt_pk_f32_fp8_sdwa v[44:45], v172 src0_sel:WORD_1
	v_cvt_pk_f32_fp8_e32 v[46:47], v173
	v_cvt_pk_f32_fp8_sdwa v[48:49], v173 src0_sel:WORD_1
	v_cvt_pk_f32_fp8_e32 v[50:51], v174
	v_cvt_pk_f32_fp8_sdwa v[52:53], v174 src0_sel:WORD_1
	v_cvt_pk_f32_fp8_e32 v[54:55], v175
	v_cvt_pk_f32_fp8_sdwa v[56:57], v175 src0_sel:WORD_1
	global_load_dwordx4 v[168:171], v80, s[12:13]
	global_load_dwordx4 v[172:175], v81, s[12:13]
	v_pk_mul_f32 v[58:59], v[26:27], v[10:11]
	v_pk_mul_f32 v[60:61], v[42:43], v[10:11]
	v_pk_mul_f32 v[196:197], v[28:29], v[12:13]
	v_pk_mul_f32 v[198:199], v[44:45], v[12:13]
	v_pk_fma_f32 v[58:59], v[30:31], v[14:15], v[58:59]
	v_pk_fma_f32 v[60:61], v[46:47], v[14:15], v[60:61]
	v_pk_fma_f32 v[196:197], v[32:33], v[16:17], v[196:197]
	v_pk_fma_f32 v[198:199], v[48:49], v[16:17], v[198:199]
	v_pk_fma_f32 v[58:59], v[34:35], v[18:19], v[58:59]
	v_pk_fma_f32 v[60:61], v[50:51], v[18:19], v[60:61]
	v_pk_fma_f32 v[196:197], v[36:37], v[20:21], v[196:197]
	v_pk_fma_f32 v[198:199], v[52:53], v[20:21], v[198:199]
	v_pk_fma_f32 v[58:59], v[38:39], v[22:23], v[58:59]
	v_pk_fma_f32 v[60:61], v[54:55], v[22:23], v[60:61]
	v_pk_fma_f32 v[196:197], v[40:41], v[24:25], v[196:197]
	v_pk_fma_f32 v[198:199], v[56:57], v[24:25], v[198:199]
	v_pk_add_f32 v[58:59], v[58:59], v[196:197]
	v_pk_add_f32 v[60:61], v[60:61], v[198:199]
	v_add_f32_e32 v62, v58, v59
	v_add_f32_e32 v63, v60, v61
	s_waitcnt vmcnt(20)
	v_cvt_pk_f32_fp8_e32 v[26:27], v188
	v_cvt_pk_f32_fp8_sdwa v[28:29], v188 src0_sel:WORD_1
	v_cvt_pk_f32_fp8_e32 v[30:31], v189
	v_cvt_pk_f32_fp8_sdwa v[32:33], v189 src0_sel:WORD_1
	v_cvt_pk_f32_fp8_e32 v[34:35], v190
	v_cvt_pk_f32_fp8_sdwa v[36:37], v190 src0_sel:WORD_1
	v_cvt_pk_f32_fp8_e32 v[38:39], v191
	v_cvt_pk_f32_fp8_sdwa v[40:41], v191 src0_sel:WORD_1
	v_cvt_pk_f32_fp8_e32 v[42:43], v192
	v_cvt_pk_f32_fp8_sdwa v[44:45], v192 src0_sel:WORD_1
	v_cvt_pk_f32_fp8_e32 v[46:47], v193
	v_cvt_pk_f32_fp8_sdwa v[48:49], v193 src0_sel:WORD_1
	v_cvt_pk_f32_fp8_e32 v[50:51], v194
	v_cvt_pk_f32_fp8_sdwa v[52:53], v194 src0_sel:WORD_1
	v_cvt_pk_f32_fp8_e32 v[54:55], v195
	v_cvt_pk_f32_fp8_sdwa v[56:57], v195 src0_sel:WORD_1
	global_load_dwordx4 v[188:191], v82, s[12:13]
	global_load_dwordx4 v[192:195], v83, s[12:13]
	v_pk_mul_f32 v[58:59], v[26:27], v[10:11]
	v_pk_mul_f32 v[60:61], v[42:43], v[10:11]
	v_pk_mul_f32 v[196:197], v[28:29], v[12:13]
	v_pk_mul_f32 v[198:199], v[44:45], v[12:13]
	v_pk_fma_f32 v[58:59], v[30:31], v[14:15], v[58:59]
	v_pk_fma_f32 v[60:61], v[46:47], v[14:15], v[60:61]
	v_pk_fma_f32 v[196:197], v[32:33], v[16:17], v[196:197]
	v_pk_fma_f32 v[198:199], v[48:49], v[16:17], v[198:199]
	v_pk_fma_f32 v[58:59], v[34:35], v[18:19], v[58:59]
	v_pk_fma_f32 v[60:61], v[50:51], v[18:19], v[60:61]
	v_pk_fma_f32 v[196:197], v[36:37], v[20:21], v[196:197]
	v_pk_fma_f32 v[198:199], v[52:53], v[20:21], v[198:199]
	v_pk_fma_f32 v[58:59], v[38:39], v[22:23], v[58:59]
	v_pk_fma_f32 v[60:61], v[54:55], v[22:23], v[60:61]
	v_pk_fma_f32 v[196:197], v[40:41], v[24:25], v[196:197]
	v_pk_fma_f32 v[198:199], v[56:57], v[24:25], v[198:199]
	v_pk_add_f32 v[58:59], v[58:59], v[196:197]
	v_pk_add_f32 v[60:61], v[60:61], v[198:199]
	v_add_f32_e32 v64, v58, v59
	v_add_f32_e32 v65, v60, v61
	s_nop 1
	v_add_f32_dpp v104, v104, v104 quad_perm:[1,0,3,2] row_mask:0xf bank_mask:0xf
	v_add_f32_dpp v105, v105, v105 quad_perm:[1,0,3,2] row_mask:0xf bank_mask:0xf
; DEVI float gelu_f(float x) { const float u = 0.7978845608028654f * (x + 0.044715f * x * x * x); return x * __builtin_amdgcn_rcpf(1.f + __expf(-2.f * u)); }
;     ...
;     for (int m = 0; m < 16; m += 2) {
;         const u32x4_t a0 = *(const u32x4_t*)(hp + m * 64), a1 = *(const u32x4_t*)(hp + m * 64 + 64);
; #pragma unroll
;         for (int t = 0; t < NTL; ++t) FP8MM(a0, b0[t], acc[t]);
;         if (m + 2 < 16) {
; #pragma unroll
;             for (int t = 0; t < NTL; ++t) b0[t] = *(const u32x4_t*)(up[t] + (m + 2) * 64);
;         }
; #pragma unroll
;         for (int t = 0; t < NTL; ++t) FP8MM(a1, b1[t], acc[t]);
;         if (m + 3 < 16) {
; #pragma unroll
;             for (int t = 0; t < NTL; ++t) b1[t] = *(const u32x4_t*)(up[t] + (m + 3) * 64);
;         }
;     }
;     ...
; #pragma unroll
;     for (int t = 0; t < NTL; ++t) { const float lo = __shfl_xor(acc[t][0], 32); const float dot = (acc[t][0] + lo * (1.f / 32.f)) * s_u[t];
;         if (kq == 0) pl[t * 16 + n16] = (u32x2_t){(unsigned)e[t], __float_as_uint(g[t] * gelu_f(dot) * s_v[t])}; }
	v_add_f32_dpp v106, v106, v106 quad_perm:[1,0,3,2] row_mask:0xf bank_mask:0xf
	v_add_f32_dpp v107, v107, v107 quad_perm:[1,0,3,2] row_mask:0xf bank_mask:0xf
	v_add_f32_dpp v108, v108, v108 quad_perm:[1,0,3,2] row_mask:0xf bank_mask:0xf
	v_add_f32_dpp v109, v109, v109 quad_perm:[1,0,3,2] row_mask:0xf bank_mask:0xf
	v_add_f32_dpp v110, v110, v110 quad_perm:[1,0,3,2] row_mask:0xf bank_mask:0xf
	v_add_f32_dpp v111, v111, v111 quad_perm:[1,0,3,2] row_mask:0xf bank_mask:0xf
	v_add_f32_dpp v112, v112, v112 quad_perm:[1,0,3,2] row_mask:0xf bank_mask:0xf
	v_add_f32_dpp v113, v113, v113 quad_perm:[1,0,3,2] row_mask:0xf bank_mask:0xf
	v_add_f32_dpp v114, v114, v114 quad_perm:[1,0,3,2] row_mask:0xf bank_mask:0xf
	v_add_f32_dpp v115, v115, v115 quad_perm:[1,0,3,2] row_mask:0xf bank_mask:0xf
	v_add_f32_dpp v62, v62, v62 quad_perm:[1,0,3,2] row_mask:0xf bank_mask:0xf
	v_add_f32_dpp v63, v63, v63 quad_perm:[1,0,3,2] row_mask:0xf bank_mask:0xf
	v_add_f32_dpp v64, v64, v64 quad_perm:[1,0,3,2] row_mask:0xf bank_mask:0xf
	v_add_f32_dpp v65, v65, v65 quad_perm:[1,0,3,2] row_mask:0xf bank_mask:0xf
	v_add_f32_dpp v104, v104, v104 quad_perm:[2,3,0,1] row_mask:0xf bank_mask:0xf
	v_add_f32_dpp v105, v105, v105 quad_perm:[2,3,0,1] row_mask:0xf bank_mask:0xf
	v_add_f32_dpp v106, v106, v106 quad_perm:[2,3,0,1] row_mask:0xf bank_mask:0xf
	v_add_f32_dpp v107, v107, v107 quad_perm:[2,3,0,1] row_mask:0xf bank_mask:0xf
	v_add_f32_dpp v108, v108, v108 quad_perm:[2,3,0,1] row_mask:0xf bank_mask:0xf
	v_add_f32_dpp v109, v109, v109 quad_perm:[2,3,0,1] row_mask:0xf bank_mask:0xf
	v_add_f32_dpp v110, v110, v110 quad_perm:[2,3,0,1] row_mask:0xf bank_mask:0xf
	v_add_f32_dpp v111, v111, v111 quad_perm:[2,3,0,1] row_mask:0xf bank_mask:0xf
	v_add_f32_dpp v112, v112, v112 quad_perm:[2,3,0,1] row_mask:0xf bank_mask:0xf
	v_add_f32_dpp v113, v113, v113 quad_perm:[2,3,0,1] row_mask:0xf bank_mask:0xf
	v_add_f32_dpp v114, v114, v114 quad_perm:[2,3,0,1] row_mask:0xf bank_mask:0xf
	v_add_f32_dpp v115, v115, v115 quad_perm:[2,3,0,1] row_mask:0xf bank_mask:0xf
	v_add_f32_dpp v62, v62, v62 quad_perm:[2,3,0,1] row_mask:0xf bank_mask:0xf
	v_add_f32_dpp v63, v63, v63 quad_perm:[2,3,0,1] row_mask:0xf bank_mask:0xf
	v_add_f32_dpp v64, v64, v64 quad_perm:[2,3,0,1] row_mask:0xf bank_mask:0xf
	v_add_f32_dpp v65, v65, v65 quad_perm:[2,3,0,1] row_mask:0xf bank_mask:0xf
	v_add_f32_dpp v104, v104, v104 row_half_mirror row_mask:0xf bank_mask:0xf
	v_add_f32_dpp v105, v105, v105 row_half_mirror row_mask:0xf bank_mask:0xf
	v_add_f32_dpp v106, v106, v106 row_half_mirror row_mask:0xf bank_mask:0xf
	v_add_f32_dpp v107, v107, v107 row_half_mirror row_mask:0xf bank_mask:0xf
	v_add_f32_dpp v108, v108, v108 row_half_mirror row_mask:0xf bank_mask:0xf
	v_add_f32_dpp v109, v109, v109 row_half_mirror row_mask:0xf bank_mask:0xf
	v_add_f32_dpp v110, v110, v110 row_half_mirror row_mask:0xf bank_mask:0xf
	v_add_f32_dpp v111, v111, v111 row_half_mirror row_mask:0xf bank_mask:0xf
	v_add_f32_dpp v112, v112, v112 row_half_mirror row_mask:0xf bank_mask:0xf
	v_add_f32_dpp v113, v113, v113 row_half_mirror row_mask:0xf bank_mask:0xf
	v_add_f32_dpp v114, v114, v114 row_half_mirror row_mask:0xf bank_mask:0xf
	v_add_f32_dpp v115, v115, v115 row_half_mirror row_mask:0xf bank_mask:0xf
	v_add_f32_dpp v62, v62, v62 row_half_mirror row_mask:0xf bank_mask:0xf
	v_add_f32_dpp v63, v63, v63 row_half_mirror row_mask:0xf bank_mask:0xf
	v_add_f32_dpp v64, v64, v64 row_half_mirror row_mask:0xf bank_mask:0xf
	v_add_f32_dpp v65, v65, v65 row_half_mirror row_mask:0xf bank_mask:0xf
	v_cndmask_b32_e64 v118, v118, v104, s[24:25]
	v_cndmask_b32_e64 v119, v119, v105, s[24:25]
	v_cndmask_b32_e64 v118, v118, v106, s[26:27]
	v_cndmask_b32_e64 v119, v119, v107, s[26:27]
	v_cndmask_b32_e64 v118, v118, v108, s[28:29]
	v_cndmask_b32_e64 v119, v119, v109, s[28:29]
	v_cndmask_b32_e64 v118, v118, v110, s[30:31]
	v_cndmask_b32_e64 v119, v119, v111, s[30:31]
	v_cndmask_b32_e64 v118, v118, v112, s[40:41]
	v_cndmask_b32_e64 v119, v119, v113, s[40:41]
	v_cndmask_b32_e64 v118, v118, v114, s[42:43]
	v_cndmask_b32_e64 v119, v119, v115, s[42:43]
	v_cndmask_b32_e64 v118, v118, v62, s[44:45]
	v_cndmask_b32_e64 v119, v119, v63, s[44:45]
	v_cndmask_b32_e64 v118, v118, v64, s[54:55]
	v_cndmask_b32_e64 v119, v119, v65, s[54:55]
	s_and_b32 s9, s22, 7
	s_lshl_b32 s9, s9, 10
	v_add_u32_e32 v7, s9, v6
	ds_add_f32 v7, v118 offset:4
	ds_add_f32 v7, v119 offset:12
	s_add_u32 s22, s22, 1
	s_cmp_lg_u32 s22, 64
	s_cbranch_scc1 .Lg1_loop
;     DEVI int* eidx() const { return (int*)(ws + WS_EIDX); }
; DEVI float gelu_f(float x) { const float u = 0.7978845608028654f * (x + 0.044715f * x * x * x); return x * __builtin_amdgcn_rcpf(1.f + __expf(-2.f * u)); }
;     ...
;     for (int t = 0; t < NTL; ++t) { e[t] = eidx[(size_t)r * 128 + (tbase + t) * 16 + n16]; g[t] = gwv[(size_t)r * 128 + (tbase + t) * 16 + n16]; }
; #pragma unroll
;     for (int t = 0; t < NTL; ++t) { s_u[t] = su[e[t]]; s_v[t] = sv[e[t]]; }
;     ...
;     for (int t = 0; t < NTL; ++t) { const float lo = __shfl_xor(acc[t][0], 32); const float dot = (acc[t][0] + lo * (1.f / 32.f)) * s_u[t];
;         if (kq == 0) pl[t * 16 + n16] = (u32x2_t){(unsigned)e[t], __float_as_uint(g[t] * gelu_f(dot) * s_v[t])}; }
	s_waitcnt vmcnt(0) lgkmcnt(0)
	s_lshl_b32 s9, s48, 9
	s_lshl_b32 s20, s34, 9
	s_add_u32 s10, s6, 0x1b292100
	s_addc_u32 s11, s7, 0
	s_add_u32 s10, s10, s9
	s_addc_u32 s11, s11, 0
	s_add_u32 s12, s6, 0x1bb12100
	s_addc_u32 s13, s7, 0
	s_add_u32 s12, s12, s9
	s_addc_u32 s13, s13, 0
	s_lshl_b32 s9, s8, 16
	s_add_u32 s16, s6, 0x2fa42100
	s_addc_u32 s17, s7, 0
	s_add_u32 s16, s16, s9
	s_addc_u32 s17, s17, 0
	s_add_u32 s18, s16, 0x40000
	s_addc_u32 s19, s17, 0
	v_lshlrev_b32_e32 v2, 3, v1
	v_lshl_add_u32 v3, v1, 4, s85
	ds_read_b128 v[68:71], v3 offset:0
	ds_read_b128 v[72:75], v3 offset:1024
	ds_read_b128 v[76:79], v3 offset:2048
	ds_read_b128 v[80:83], v3 offset:3072
	ds_read_b128 v[84:87], v3 offset:4096
	ds_read_b128 v[88:91], v3 offset:5120
	ds_read_b128 v[92:95], v3 offset:6144
	ds_read_b128 v[96:99], v3 offset:7168
	global_load_dwordx2 v[20:21], v2, s[10:11]
	global_load_dwordx2 v[22:23], v2, s[12:13]
	s_add_u32 s10, s10, s20
	s_addc_u32 s11, s11, 0
	s_add_u32 s12, s12, s20
	s_addc_u32 s13, s13, 0
	global_load_dwordx2 v[24:25], v2, s[10:11]
	global_load_dwordx2 v[26:27], v2, s[12:13]
	s_add_u32 s10, s10, s20
	s_addc_u32 s11, s11, 0
	s_add_u32 s12, s12, s20
	s_addc_u32 s13, s13, 0
	global_load_dwordx2 v[28:29], v2, s[10:11]
	global_load_dwordx2 v[30:31], v2, s[12:13]
	s_add_u32 s10, s10, s20
	s_addc_u32 s11, s11, 0
	s_add_u32 s12, s12, s20
	s_addc_u32 s13, s13, 0
	global_load_dwordx2 v[32:33], v2, s[10:11]
	global_load_dwordx2 v[34:35], v2, s[12:13]
	s_add_u32 s10, s10, s20
	s_addc_u32 s11, s11, 0
	s_add_u32 s12, s12, s20
	s_addc_u32 s13, s13, 0
	global_load_dwordx2 v[36:37], v2, s[10:11]
	global_load_dwordx2 v[38:39], v2, s[12:13]
	s_add_u32 s10, s10, s20
	s_addc_u32 s11, s11, 0
	s_add_u32 s12, s12, s20
	s_addc_u32 s13, s13, 0
	global_load_dwordx2 v[40:41], v2, s[10:11]
	global_load_dwordx2 v[42:43], v2, s[12:13]
	s_add_u32 s10, s10, s20
	s_addc_u32 s11, s11, 0
	s_add_u32 s12, s12, s20
	s_addc_u32 s13, s13, 0
	global_load_dwordx2 v[44:45], v2, s[10:11]
	global_load_dwordx2 v[46:47], v2, s[12:13]
	s_add_u32 s10, s10, s20
	s_addc_u32 s11, s11, 0
	s_add_u32 s12, s12, s20
	s_addc_u32 s13, s13, 0
	global_load_dwordx2 v[48:49], v2, s[10:11]
	global_load_dwordx2 v[50:51], v2, s[12:13]
	s_add_u32 s10, s10, s20
	s_addc_u32 s11, s11, 0
	s_add_u32 s12, s12, s20
	s_addc_u32 s13, s13, 0
	s_waitcnt vmcnt(15)
	v_lshlrev_b32_e32 v4, 2, v20
	v_lshlrev_b32_e32 v5, 2, v21
	global_load_dword v120, v4, s[16:17]
	global_load_dword v121, v5, s[16:17]
	global_load_dword v122, v4, s[18:19]
	global_load_dword v123, v5, s[18:19]
	s_waitcnt vmcnt(17)
	v_lshlrev_b32_e32 v4, 2, v24
	v_lshlrev_b32_e32 v5, 2, v25
	global_load_dword v124, v4, s[16:17]
	global_load_dword v125, v5, s[16:17]
	global_load_dword v126, v4, s[18:19]
	global_load_dword v127, v5, s[18:19]
	s_waitcnt vmcnt(19)
	v_lshlrev_b32_e32 v4, 2, v28
	v_lshlrev_b32_e32 v5, 2, v29
	global_load_dword v128, v4, s[16:17]
	global_load_dword v129, v5, s[16:17]
	global_load_dword v130, v4, s[18:19]
	global_load_dword v131, v5, s[18:19]
	s_waitcnt vmcnt(21)
	v_lshlrev_b32_e32 v4, 2, v32
	v_lshlrev_b32_e32 v5, 2, v33
	global_load_dword v132, v4, s[16:17]
	global_load_dword v133, v5, s[16:17]
	global_load_dword v134, v4, s[18:19]
	global_load_dword v135, v5, s[18:19]
	s_waitcnt vmcnt(23)
	v_lshlrev_b32_e32 v4, 2, v36
	v_lshlrev_b32_e32 v5, 2, v37
	global_load_dword v136, v4, s[16:17]
	global_load_dword v137, v5, s[16:17]
	global_load_dword v138, v4, s[18:19]
	global_load_dword v139, v5, s[18:19]
	s_waitcnt vmcnt(25)
	v_lshlrev_b32_e32 v4, 2, v40
	v_lshlrev_b32_e32 v5, 2, v41
	global_load_dword v140, v4, s[16:17]
	global_load_dword v141, v5, s[16:17]
	global_load_dword v142, v4, s[18:19]
	global_load_dword v143, v5, s[18:19]
	s_waitcnt vmcnt(27)
	v_lshlrev_b32_e32 v4, 2, v44
	v_lshlrev_b32_e32 v5, 2, v45
	global_load_dword v144, v4, s[16:17]
	global_load_dword v145, v5, s[16:17]
	global_load_dword v146, v4, s[18:19]
	global_load_dword v147, v5, s[18:19]
	s_waitcnt vmcnt(29)
	v_lshlrev_b32_e32 v4, 2, v48
	v_lshlrev_b32_e32 v5, 2, v49
	global_load_dword v148, v4, s[16:17]
	global_load_dword v149, v5, s[16:17]
	global_load_dword v150, v4, s[18:19]
	global_load_dword v151, v5, s[18:19]
	s_waitcnt lgkmcnt(0)
	s_waitcnt vmcnt(28)
	v_mul_f32_e32 v69, v69, v120
	v_mul_f32_e32 v6, 0x3d372713, v69
	v_mul_f32_e32 v6, v69, v6
	v_fma_f32 v6, v69, v6, v69
	v_mul_f32_e32 v6, 0x3f4c422a, v6
	v_mul_f32_e32 v6, -2.0, v6
	v_mul_f32_e32 v6, 0x3fb8aa3b, v6
	v_exp_f32_e32 v6, v6
	s_nop 0
	v_add_f32_e32 v6, 1.0, v6
	v_rcp_f32_e32 v6, v6
	s_nop 0
	v_mul_f32_e32 v69, v69, v6
	v_mul_f32_e32 v69, v22, v69
	v_mul_f32_e32 v69, v122, v69
	v_mul_f32_e32 v71, v71, v121
	v_mul_f32_e32 v7, 0x3d372713, v71
	v_mul_f32_e32 v7, v71, v7
	v_fma_f32 v7, v71, v7, v71
	v_mul_f32_e32 v7, 0x3f4c422a, v7
	v_mul_f32_e32 v7, -2.0, v7
	v_mul_f32_e32 v7, 0x3fb8aa3b, v7
	v_exp_f32_e32 v7, v7
	s_nop 0
	v_add_f32_e32 v7, 1.0, v7
	v_rcp_f32_e32 v7, v7
	s_nop 0
	v_mul_f32_e32 v71, v71, v7
	v_mul_f32_e32 v71, v23, v71
	v_mul_f32_e32 v71, v123, v71
	v_mov_b32_e32 v68, v20
	v_mov_b32_e32 v70, v21
	ds_write_b128 v3, v[68:71] offset:0
	s_waitcnt vmcnt(24)
	v_mul_f32_e32 v73, v73, v124
	v_mul_f32_e32 v6, 0x3d372713, v73
	v_mul_f32_e32 v6, v73, v6
	v_fma_f32 v6, v73, v6, v73
	v_mul_f32_e32 v6, 0x3f4c422a, v6
	v_mul_f32_e32 v6, -2.0, v6
	v_mul_f32_e32 v6, 0x3fb8aa3b, v6
	v_exp_f32_e32 v6, v6
	s_nop 0
	v_add_f32_e32 v6, 1.0, v6
	v_rcp_f32_e32 v6, v6
	s_nop 0
	v_mul_f32_e32 v73, v73, v6
	v_mul_f32_e32 v73, v26, v73
	v_mul_f32_e32 v73, v126, v73
	v_mul_f32_e32 v75, v75, v125
	v_mul_f32_e32 v7, 0x3d372713, v75
	v_mul_f32_e32 v7, v75, v7
	v_fma_f32 v7, v75, v7, v75
	v_mul_f32_e32 v7, 0x3f4c422a, v7
	v_mul_f32_e32 v7, -2.0, v7
	v_mul_f32_e32 v7, 0x3fb8aa3b, v7
	v_exp_f32_e32 v7, v7
	s_nop 0
	v_add_f32_e32 v7, 1.0, v7
	v_rcp_f32_e32 v7, v7
	s_nop 0
	v_mul_f32_e32 v75, v75, v7
	v_mul_f32_e32 v75, v27, v75
	v_mul_f32_e32 v75, v127, v75
	v_mov_b32_e32 v72, v24
	v_mov_b32_e32 v74, v25
	ds_write_b128 v3, v[72:75] offset:1024
	s_waitcnt vmcnt(20)
; DEVI float gelu_f(float x) { const float u = 0.7978845608028654f * (x + 0.044715f * x * x * x); return x * __builtin_amdgcn_rcpf(1.f + __expf(-2.f * u)); }
;     ...
;     for (int t = 0; t < NTL; ++t) { const float lo = __shfl_xor(acc[t][0], 32); const float dot = (acc[t][0] + lo * (1.f / 32.f)) * s_u[t];
;         if (kq == 0) pl[t * 16 + n16] = (u32x2_t){(unsigned)e[t], __float_as_uint(g[t] * gelu_f(dot) * s_v[t])}; }
	v_mul_f32_e32 v77, v77, v128
	v_mul_f32_e32 v6, 0x3d372713, v77
	v_mul_f32_e32 v6, v77, v6
	v_fma_f32 v6, v77, v6, v77
	v_mul_f32_e32 v6, 0x3f4c422a, v6
	v_mul_f32_e32 v6, -2.0, v6
	v_mul_f32_e32 v6, 0x3fb8aa3b, v6
	v_exp_f32_e32 v6, v6
	s_nop 0
	v_add_f32_e32 v6, 1.0, v6
	v_rcp_f32_e32 v6, v6
	s_nop 0
	v_mul_f32_e32 v77, v77, v6
	v_mul_f32_e32 v77, v30, v77
	v_mul_f32_e32 v77, v130, v77
	v_mul_f32_e32 v79, v79, v129
	v_mul_f32_e32 v7, 0x3d372713, v79
	v_mul_f32_e32 v7, v79, v7
	v_fma_f32 v7, v79, v7, v79
	v_mul_f32_e32 v7, 0x3f4c422a, v7
	v_mul_f32_e32 v7, -2.0, v7
	v_mul_f32_e32 v7, 0x3fb8aa3b, v7
	v_exp_f32_e32 v7, v7
	s_nop 0
	v_add_f32_e32 v7, 1.0, v7
	v_rcp_f32_e32 v7, v7
	s_nop 0
	v_mul_f32_e32 v79, v79, v7
	v_mul_f32_e32 v79, v31, v79
	v_mul_f32_e32 v79, v131, v79
	v_mov_b32_e32 v76, v28
	v_mov_b32_e32 v78, v29
	ds_write_b128 v3, v[76:79] offset:2048
	s_waitcnt vmcnt(16)
	v_mul_f32_e32 v81, v81, v132
	v_mul_f32_e32 v6, 0x3d372713, v81
	v_mul_f32_e32 v6, v81, v6
	v_fma_f32 v6, v81, v6, v81
	v_mul_f32_e32 v6, 0x3f4c422a, v6
	v_mul_f32_e32 v6, -2.0, v6
	v_mul_f32_e32 v6, 0x3fb8aa3b, v6
	v_exp_f32_e32 v6, v6
	s_nop 0
	v_add_f32_e32 v6, 1.0, v6
	v_rcp_f32_e32 v6, v6
	s_nop 0
	v_mul_f32_e32 v81, v81, v6
	v_mul_f32_e32 v81, v34, v81
	v_mul_f32_e32 v81, v134, v81
	v_mul_f32_e32 v83, v83, v133
	v_mul_f32_e32 v7, 0x3d372713, v83
	v_mul_f32_e32 v7, v83, v7
	v_fma_f32 v7, v83, v7, v83
	v_mul_f32_e32 v7, 0x3f4c422a, v7
	v_mul_f32_e32 v7, -2.0, v7
	v_mul_f32_e32 v7, 0x3fb8aa3b, v7
	v_exp_f32_e32 v7, v7
	s_nop 0
	v_add_f32_e32 v7, 1.0, v7
	v_rcp_f32_e32 v7, v7
	s_nop 0
	v_mul_f32_e32 v83, v83, v7
	v_mul_f32_e32 v83, v35, v83
	v_mul_f32_e32 v83, v135, v83
	v_mov_b32_e32 v80, v32
	v_mov_b32_e32 v82, v33
	ds_write_b128 v3, v[80:83] offset:3072
	s_waitcnt vmcnt(12)
	v_mul_f32_e32 v85, v85, v136
	v_mul_f32_e32 v6, 0x3d372713, v85
	v_mul_f32_e32 v6, v85, v6
	v_fma_f32 v6, v85, v6, v85
	v_mul_f32_e32 v6, 0x3f4c422a, v6
	v_mul_f32_e32 v6, -2.0, v6
	v_mul_f32_e32 v6, 0x3fb8aa3b, v6
	v_exp_f32_e32 v6, v6
	s_nop 0
	v_add_f32_e32 v6, 1.0, v6
	v_rcp_f32_e32 v6, v6
	s_nop 0
	v_mul_f32_e32 v85, v85, v6
	v_mul_f32_e32 v85, v38, v85
	v_mul_f32_e32 v85, v138, v85
	v_mul_f32_e32 v87, v87, v137
	v_mul_f32_e32 v7, 0x3d372713, v87
	v_mul_f32_e32 v7, v87, v7
	v_fma_f32 v7, v87, v7, v87
	v_mul_f32_e32 v7, 0x3f4c422a, v7
	v_mul_f32_e32 v7, -2.0, v7
	v_mul_f32_e32 v7, 0x3fb8aa3b, v7
	v_exp_f32_e32 v7, v7
	s_nop 0
	v_add_f32_e32 v7, 1.0, v7
	v_rcp_f32_e32 v7, v7
	s_nop 0
	v_mul_f32_e32 v87, v87, v7
	v_mul_f32_e32 v87, v39, v87
	v_mul_f32_e32 v87, v139, v87
	v_mov_b32_e32 v84, v36
	v_mov_b32_e32 v86, v37
	ds_write_b128 v3, v[84:87] offset:4096
	s_waitcnt vmcnt(8)
	v_mul_f32_e32 v89, v89, v140
	v_mul_f32_e32 v6, 0x3d372713, v89
	v_mul_f32_e32 v6, v89, v6
	v_fma_f32 v6, v89, v6, v89
	v_mul_f32_e32 v6, 0x3f4c422a, v6
	v_mul_f32_e32 v6, -2.0, v6
	v_mul_f32_e32 v6, 0x3fb8aa3b, v6
	v_exp_f32_e32 v6, v6
	s_nop 0
	v_add_f32_e32 v6, 1.0, v6
	v_rcp_f32_e32 v6, v6
	s_nop 0
	v_mul_f32_e32 v89, v89, v6
	v_mul_f32_e32 v89, v42, v89
	v_mul_f32_e32 v89, v142, v89
	v_mul_f32_e32 v91, v91, v141
	v_mul_f32_e32 v7, 0x3d372713, v91
	v_mul_f32_e32 v7, v91, v7
	v_fma_f32 v7, v91, v7, v91
	v_mul_f32_e32 v7, 0x3f4c422a, v7
	v_mul_f32_e32 v7, -2.0, v7
	v_mul_f32_e32 v7, 0x3fb8aa3b, v7
	v_exp_f32_e32 v7, v7
	s_nop 0
	v_add_f32_e32 v7, 1.0, v7
	v_rcp_f32_e32 v7, v7
	s_nop 0
	v_mul_f32_e32 v91, v91, v7
	v_mul_f32_e32 v91, v43, v91
	v_mul_f32_e32 v91, v143, v91
	v_mov_b32_e32 v88, v40
	v_mov_b32_e32 v90, v41
	ds_write_b128 v3, v[88:91] offset:5120
	s_waitcnt vmcnt(4)
; DEVI float gelu_f(float x) { const float u = 0.7978845608028654f * (x + 0.044715f * x * x * x); return x * __builtin_amdgcn_rcpf(1.f + __expf(-2.f * u)); }
;     ...
;     for (int t = 0; t < NTL; ++t) { const float lo = __shfl_xor(acc[t][0], 32); const float dot = (acc[t][0] + lo * (1.f / 32.f)) * s_u[t];
;         if (kq == 0) pl[t * 16 + n16] = (u32x2_t){(unsigned)e[t], __float_as_uint(g[t] * gelu_f(dot) * s_v[t])}; }
;     ...
;     for (int j0 = 0; j0 < NTL * 16; j0 += 16) {
;         u32x4_t w[16]; float cj[16];
; #pragma unroll
;         for (int jj = 0; jj < 16; ++jj) { const u32x2_t pr = pl[j0 + jj]; const int ej = __builtin_amdgcn_readfirstlane((int)pr.x); cj[jj] = __uint_as_float(pr.y);
;             w[jj] = *(const u32x4_t*)(v8 + (size_t)ej * D + 16 * lane); }
	v_mul_f32_e32 v93, v93, v144
	v_mul_f32_e32 v6, 0x3d372713, v93
	v_mul_f32_e32 v6, v93, v6
	v_fma_f32 v6, v93, v6, v93
	v_mul_f32_e32 v6, 0x3f4c422a, v6
	v_mul_f32_e32 v6, -2.0, v6
	v_mul_f32_e32 v6, 0x3fb8aa3b, v6
	v_exp_f32_e32 v6, v6
	s_nop 0
	v_add_f32_e32 v6, 1.0, v6
	v_rcp_f32_e32 v6, v6
	s_nop 0
	v_mul_f32_e32 v93, v93, v6
	v_mul_f32_e32 v93, v46, v93
	v_mul_f32_e32 v93, v146, v93
	v_mul_f32_e32 v95, v95, v145
	v_mul_f32_e32 v7, 0x3d372713, v95
	v_mul_f32_e32 v7, v95, v7
	v_fma_f32 v7, v95, v7, v95
	v_mul_f32_e32 v7, 0x3f4c422a, v7
	v_mul_f32_e32 v7, -2.0, v7
	v_mul_f32_e32 v7, 0x3fb8aa3b, v7
	v_exp_f32_e32 v7, v7
	s_nop 0
	v_add_f32_e32 v7, 1.0, v7
	v_rcp_f32_e32 v7, v7
	s_nop 0
	v_mul_f32_e32 v95, v95, v7
	v_mul_f32_e32 v95, v47, v95
	v_mul_f32_e32 v95, v147, v95
	v_mov_b32_e32 v92, v44
	v_mov_b32_e32 v94, v45
	ds_write_b128 v3, v[92:95] offset:6144
	s_waitcnt vmcnt(0)
	v_mul_f32_e32 v97, v97, v148
	v_mul_f32_e32 v6, 0x3d372713, v97
	v_mul_f32_e32 v6, v97, v6
	v_fma_f32 v6, v97, v6, v97
	v_mul_f32_e32 v6, 0x3f4c422a, v6
	v_mul_f32_e32 v6, -2.0, v6
	v_mul_f32_e32 v6, 0x3fb8aa3b, v6
	v_exp_f32_e32 v6, v6
	s_nop 0
	v_add_f32_e32 v6, 1.0, v6
	v_rcp_f32_e32 v6, v6
	s_nop 0
	v_mul_f32_e32 v97, v97, v6
	v_mul_f32_e32 v97, v50, v97
	v_mul_f32_e32 v97, v150, v97
	v_mul_f32_e32 v99, v99, v149
	v_mul_f32_e32 v7, 0x3d372713, v99
	v_mul_f32_e32 v7, v99, v7
	v_fma_f32 v7, v99, v7, v99
	v_mul_f32_e32 v7, 0x3f4c422a, v7
	v_mul_f32_e32 v7, -2.0, v7
	v_mul_f32_e32 v7, 0x3fb8aa3b, v7
	v_exp_f32_e32 v7, v7
	s_nop 0
	v_add_f32_e32 v7, 1.0, v7
	v_rcp_f32_e32 v7, v7
	s_nop 0
	v_mul_f32_e32 v99, v99, v7
	v_mul_f32_e32 v99, v51, v99
	v_mul_f32_e32 v99, v151, v99
	v_mov_b32_e32 v96, v48
	v_mov_b32_e32 v98, v49
	ds_write_b128 v3, v[96:99] offset:7168
	s_waitcnt lgkmcnt(0)
	v_cmp_gt_u32_e32 vcc, 8, v116
	s_nop 1
	s_lshl_b32 s20, s34, 12
	s_lshl_b32 s11, s8, 24
	s_add_u32 s56, s6, 0x27a42100
	s_addc_u32 s57, s7, 0
	s_add_u32 s56, s56, s11
	s_addc_u32 s57, s57, 0
	s_mov_b32 s12, s56
	s_mov_b32 s13, s57
	s_lshl_b32 s11, s48, 12
	s_add_u32 s58, s4, s11
	s_addc_u32 s59, s5, 0
	s_mul_i32 s11, s8, 0x6c000
	s_add_u32 s60, s6, 0x9000
	s_addc_u32 s61, s7, 0
	s_add_u32 s60, s60, s11
	s_addc_u32 s61, s61, 0
	s_mov_b32 s24, 0xff00ff00
	s_mov_b32 s25, 0xff00ff00
	v_and_b32_e32 v2, 7, v1
	v_lshrrev_b32_e32 v3, 3, v1
	v_lshlrev_b32_e32 v4, 4, v2
	v_lshlrev_b32_e32 v5, 7, v3
	v_add_u32_e32 v5, s85, v5
	v_lshlrev_b32_e32 v6, 6, v2
	v_lshl_add_u32 v6, v3, 3, v6
	ds_read_b128 v[26:29], v5 offset:0
	ds_read_b128 v[30:33], v5 offset:16
	ds_read_b128 v[34:37], v5 offset:32
	ds_read_b128 v[38:41], v5 offset:48
	ds_read_b128 v[42:45], v5 offset:64
	ds_read_b128 v[46:49], v5 offset:80
	ds_read_b128 v[50:53], v5 offset:96
	ds_read_b128 v[54:57], v5 offset:112
	s_waitcnt lgkmcnt(0)
	v_lshl_add_u32 v68, v26, 10, v4
	v_lshl_add_u32 v69, v28, 10, v4
	v_lshl_add_u32 v70, v30, 10, v4
	v_lshl_add_u32 v71, v32, 10, v4
	v_lshl_add_u32 v72, v34, 10, v4
	v_lshl_add_u32 v73, v36, 10, v4
	v_lshl_add_u32 v74, v38, 10, v4
	v_lshl_add_u32 v75, v40, 10, v4
	v_lshl_add_u32 v76, v42, 10, v4
	v_lshl_add_u32 v77, v44, 10, v4
	v_lshl_add_u32 v78, v46, 10, v4
	v_lshl_add_u32 v79, v48, 10, v4
	v_lshl_add_u32 v80, v50, 10, v4
	v_lshl_add_u32 v81, v52, 10, v4
	v_lshl_add_u32 v82, v54, 10, v4
	v_lshl_add_u32 v83, v56, 10, v4
	global_load_dwordx4 v[120:123], v68, s[12:13]
	global_load_dwordx4 v[124:127], v69, s[12:13]
	global_load_dwordx4 v[128:131], v70, s[12:13]
	global_load_dwordx4 v[132:135], v71, s[12:13]
	global_load_dwordx4 v[136:139], v72, s[12:13]
	global_load_dwordx4 v[140:143], v73, s[12:13]
	global_load_dwordx4 v[144:147], v74, s[12:13]
	global_load_dwordx4 v[148:151], v75, s[12:13]
	global_load_dwordx4 v[152:155], v76, s[12:13]
	global_load_dwordx4 v[156:159], v77, s[12:13]
	global_load_dwordx4 v[160:163], v78, s[12:13]
	global_load_dwordx4 v[164:167], v79, s[12:13]
	global_load_dwordx4 v[168:171], v80, s[12:13]
	global_load_dwordx4 v[172:175], v81, s[12:13]
	global_load_dwordx4 v[188:191], v82, s[12:13]
	global_load_dwordx4 v[192:195], v83, s[12:13]
	s_mov_b32 s22, 0
